# kv up-projection epilogue: first-pass row-sumsq loads hoisted with counted vmcnt; attention interior loop back-edge rotation (slot rotation + next K read base computed before the loop-back barrier)
# speedup vs baseline: 1.0039x; 1.0039x over previous
.Lattn_rot:
	ds_read_b128 v[48:51], v52
	ds_read_b128 v[106:109], v52 offset:32
	ds_read_b128 v[64:67], v52 offset:6144
	ds_read_b128 v[110:113], v52 offset:6176
	ds_read_b128 v[114:117], v52 offset:64
	ds_read_b128 v[118:121], v52 offset:96
	ds_read_b128 v[122:125], v52 offset:6208
	ds_read_b128 v[126:129], v52 offset:6240
	v_add_u32_e32 v52, s52, v150
	ds_read_b128 v[132:135], v52
	ds_read_b128 v[160:163], v52 offset:6144
	v_add_u32_e32 v52, s52, v151
	ds_read_b128 v[164:167], v52
	ds_read_b128 v[168:171], v52 offset:6144
	s_add_i32 s4, s49, 2
	s_cmp_lt_u32 s4, s36
	s_cselect_b32 s4, s4, s48
	s_mul_i32 s14, s4, 0x3000
	s_mul_hi_u32 s15, s4, 0x3000
	s_add_u32 s14, s6, s14
	s_mul_i32 s52, s37, 0x3000
	s_addc_u32 s15, s7, s15
	s_add_i32 s52, s33, s52
	v_lshl_add_u64 v[172:173], v[144:145], 1, s[14:15]
	s_mov_b32 m0, s52
	s_andn2_b64 vcc, exec, s[10:11]
	global_load_lds_dwordx4 v[172:173], off
	s_cbranch_vccnz .LBB0_106
	v_lshl_add_u64 v[172:173], v[80:81], 1, s[14:15]
	s_add_i32 m0, s52, 0x2000
	s_nop 0
	global_load_lds_dwordx4 v[172:173], off

.LBB0_110:
	s_add_i32 s49, s49, 1
	s_cmp_eq_u32 s42, s49
	s_cselect_b32 s13, s13, s45
	s_cselect_b32 s45, s45, s37
	s_cselect_b32 s37, s37, s43
	s_cselect_b32 s43, s43, s13
	s_mul_i32 s52, s43, 0x3000
	s_bitset1_b32 s52, 4
	v_add_u32_e32 v52, s52, v149
	s_barrier
	s_cbranch_scc1 .LBB0_113
	s_branch .Lattn_rot

.LBB0_953:
	s_cmp_lt_i32 s66, 3
	s_mov_b64 s[0:1], -1
	s_cbranch_scc1 .LBB0_1091
	s_cmp_gt_i32 s66, 3
	s_cbranch_scc0 .LBB0_1088
	s_waitcnt lgkmcnt(0)
	v_mov_b32_e32 v82, v192
	s_movk_i32 s0, 0xffc0
	v_and_b32_e32 v80, 15, v82
	v_ashrrev_i32_e32 v83, 2, v82
	v_bfe_u32 v144, v82, 6, 2
	v_and_or_b32 v145, v83, s0, v80
	v_cmp_lt_u32_e64 s[40:41], 1, v144
	v_lshlrev_b32_e32 v80, 4, v145
	s_and_saveexec_b64 s[0:1], s[40:41]
	s_xor_b64 s[0:1], exec, s[0:1]
	v_lshlrev_b32_e32 v80, 4, v145
	s_or_saveexec_b64 s[0:1], s[0:1]
	v_bfe_u32 v134, v82, 4, 2
	s_xor_b64 exec, exec, s[0:1]
	s_cbranch_execz .LBB0_991
	v_xor_b32_e32 v82, 16, v195
	v_cmp_lt_i32_e32 vcc, v82, v197
	s_add_i32 s7, s30, 0x28000
	v_lshl_add_u32 v137, v144, 2, 16
	v_cndmask_b32_e32 v82, v195, v82, vcc
	v_cmp_lt_i32_e32 vcc, v196, v197
	v_lshlrev_b32_e32 v135, 2, v82
	s_nop 0
	v_cndmask_b32_e32 v82, v195, v196, vcc
	v_lshlrev_b32_e32 v136, 2, v82
	v_add_u32_e32 v82, s7, v145
	v_ashrrev_i32_e32 v83, 31, v82
	v_lshl_add_u64 v[82:83], v[82:83], 2, s[90:91]
	global_load_dword v204, v[82:83], off
	global_load_dword v205, v[82:83], off offset:64
	global_load_dword v206, v[82:83], off offset:128
	global_load_dword v207, v[82:83], off offset:192
	global_load_dword v208, v[82:83], off offset:512
	global_load_dword v209, v[82:83], off offset:576
	global_load_dword v210, v[82:83], off offset:640
	global_load_dword v211, v[82:83], off offset:704
	v_cmp_eq_u32_e32 vcc, 0, v134
	s_waitcnt vmcnt(7)
	v_fmamk_f32 v132, v204, 0x3b800000, v194
	v_cmp_gt_f32_e64 s[42:43], s19, v132
	v_mul_f32_e32 v133, 0x4b800000, v132
	s_nop 0
	v_cndmask_b32_e64 v132, v132, v133, s[42:43]
	v_rsq_f32_e32 v132, v132
	s_nop 0
	v_mul_f32_e32 v133, 0x45800000, v132
	v_cndmask_b32_e64 v132, v132, v133, s[42:43]
	v_pk_mul_f32 v[140:141], v[128:129], v[132:133] op_sel_hi:[1,0]
	v_pk_mul_f32 v[138:139], v[130:131], v[132:133] op_sel_hi:[1,0]
	v_mul_f32_e32 v133, v141, v141
	v_fmac_f32_e32 v133, v140, v140
	v_fmac_f32_e32 v133, v138, v138
	v_fmac_f32_e32 v133, v139, v139
	v_pk_mul_f32 v[140:141], v[124:125], v[132:133] op_sel_hi:[1,0]
	v_pk_mul_f32 v[138:139], v[126:127], v[132:133] op_sel_hi:[1,0]
	v_mul_f32_e32 v141, v141, v141
	v_fmac_f32_e32 v141, v140, v140
	v_fmac_f32_e32 v141, v138, v138
	v_fmac_f32_e32 v141, v139, v139
	v_add_f32_e32 v133, v133, v141
	ds_bpermute_b32 v138, v135, v133
	s_waitcnt lgkmcnt(0)
	v_add_f32_e32 v133, v133, v138
	ds_bpermute_b32 v139, v136, v133
	v_add_u32_e32 v138, v137, v80
	s_and_saveexec_b64 s[10:11], vcc
	s_cbranch_execz .LBB0_960
	s_waitcnt lgkmcnt(0)
	v_add_f32_e32 v133, v133, v139
	ds_write_b32 v138, v133 offset:32768

.LBB0_962:
	s_or_b64 exec, exec, s[10:11]
	s_nop 0
	s_waitcnt vmcnt(6)
	v_fmamk_f32 v132, v205, 0x3b800000, v194
	v_cmp_gt_f32_e64 s[42:43], s19, v132
	s_waitcnt lgkmcnt(0)
	v_mul_f32_e32 v133, 0x4b800000, v132
	v_cndmask_b32_e64 v132, v132, v133, s[42:43]
	v_rsq_f32_e32 v132, v132
	s_nop 0
	v_mul_f32_e32 v133, 0x45800000, v132
	v_cndmask_b32_e64 v132, v132, v133, s[42:43]
	v_mov_b32_e32 v133, 0x100
	v_pk_mul_f32 v[140:141], v[112:113], v[132:133] op_sel_hi:[1,0]
	v_lshl_or_b32 v142, v145, 4, v133
	v_pk_mul_f32 v[138:139], v[114:115], v[132:133] op_sel_hi:[1,0]
	v_mul_f32_e32 v133, v141, v141
	v_fmac_f32_e32 v133, v140, v140
	v_fmac_f32_e32 v133, v138, v138
	v_fmac_f32_e32 v133, v139, v139
	v_pk_mul_f32 v[140:141], v[108:109], v[132:133] op_sel_hi:[1,0]
	v_pk_mul_f32 v[138:139], v[110:111], v[132:133] op_sel_hi:[1,0]
	v_mul_f32_e32 v141, v141, v141
	v_fmac_f32_e32 v141, v140, v140
	v_fmac_f32_e32 v141, v138, v138
	v_fmac_f32_e32 v141, v139, v139
	v_add_f32_e32 v133, v133, v141
	ds_bpermute_b32 v138, v135, v133
	s_waitcnt lgkmcnt(0)
	v_add_f32_e32 v133, v133, v138
	ds_bpermute_b32 v139, v136, v133
	v_add_u32_e32 v138, v137, v142
	s_and_saveexec_b64 s[10:11], vcc
	s_cbranch_execz .LBB0_964
	s_waitcnt lgkmcnt(0)
	v_add_f32_e32 v133, v133, v139
	ds_write_b32 v138, v133 offset:32768

.LBB0_966:
	s_or_b64 exec, exec, s[10:11]
	s_nop 0
	s_waitcnt vmcnt(5)
	v_fmamk_f32 v132, v206, 0x3b800000, v194
	v_cmp_gt_f32_e64 s[42:43], s19, v132
	s_waitcnt lgkmcnt(0)
	v_mul_f32_e32 v133, 0x4b800000, v132
	v_cndmask_b32_e64 v132, v132, v133, s[42:43]
	v_rsq_f32_e32 v132, v132
	s_nop 0
	v_mul_f32_e32 v133, 0x45800000, v132
	v_cndmask_b32_e64 v132, v132, v133, s[42:43]
	v_mov_b32_e32 v133, 0x200
	v_pk_mul_f32 v[140:141], v[96:97], v[132:133] op_sel_hi:[1,0]
	v_lshl_or_b32 v142, v145, 4, v133
	v_pk_mul_f32 v[138:139], v[98:99], v[132:133] op_sel_hi:[1,0]
	v_mul_f32_e32 v133, v141, v141
	v_fmac_f32_e32 v133, v140, v140
	v_fmac_f32_e32 v133, v138, v138
	v_fmac_f32_e32 v133, v139, v139
	v_pk_mul_f32 v[140:141], v[92:93], v[132:133] op_sel_hi:[1,0]
	v_pk_mul_f32 v[138:139], v[94:95], v[132:133] op_sel_hi:[1,0]
	v_mul_f32_e32 v141, v141, v141
	v_fmac_f32_e32 v141, v140, v140
	v_fmac_f32_e32 v141, v138, v138
	v_fmac_f32_e32 v141, v139, v139
	v_add_f32_e32 v133, v133, v141
	ds_bpermute_b32 v138, v135, v133
	s_waitcnt lgkmcnt(0)
	v_add_f32_e32 v133, v133, v138
	ds_bpermute_b32 v139, v136, v133
	v_add_u32_e32 v138, v137, v142
	s_and_saveexec_b64 s[10:11], vcc
	s_cbranch_execz .LBB0_968
	s_waitcnt lgkmcnt(0)
	v_add_f32_e32 v133, v133, v139
	ds_write_b32 v138, v133 offset:32768

.LBB0_970:
	s_or_b64 exec, exec, s[10:11]
	s_nop 0
	s_waitcnt vmcnt(4)
	v_fmamk_f32 v132, v207, 0x3b800000, v194
	v_cmp_gt_f32_e64 s[42:43], s19, v132
	s_waitcnt lgkmcnt(0)
	v_mul_f32_e32 v133, 0x4b800000, v132
	v_cndmask_b32_e64 v132, v132, v133, s[42:43]
	v_rsq_f32_e32 v132, v132
	s_nop 0
	v_mul_f32_e32 v133, 0x45800000, v132
	v_cndmask_b32_e64 v132, v132, v133, s[42:43]
	v_mov_b32_e32 v133, 0x300
	v_pk_mul_f32 v[140:141], v[76:77], v[132:133] op_sel_hi:[1,0]
	v_lshl_or_b32 v142, v145, 4, v133
	v_pk_mul_f32 v[138:139], v[78:79], v[132:133] op_sel_hi:[1,0]
	v_mul_f32_e32 v133, v141, v141
	v_fmac_f32_e32 v133, v140, v140
	v_fmac_f32_e32 v133, v138, v138
	v_fmac_f32_e32 v133, v139, v139
	v_pk_mul_f32 v[140:141], v[72:73], v[132:133] op_sel_hi:[1,0]
	v_pk_mul_f32 v[138:139], v[74:75], v[132:133] op_sel_hi:[1,0]
	v_mul_f32_e32 v141, v141, v141
	v_fmac_f32_e32 v141, v140, v140
	v_fmac_f32_e32 v141, v138, v138
	v_fmac_f32_e32 v141, v139, v139
	v_add_f32_e32 v133, v133, v141
	ds_bpermute_b32 v138, v135, v133
	s_waitcnt lgkmcnt(0)
	v_add_f32_e32 v133, v133, v138
	ds_bpermute_b32 v139, v136, v133
	v_add_u32_e32 v138, v137, v142
	s_and_saveexec_b64 s[10:11], vcc
	s_cbranch_execz .LBB0_972
	s_waitcnt lgkmcnt(0)
	v_add_f32_e32 v133, v133, v139
	ds_write_b32 v138, v133 offset:32768

.LBB0_974:
	s_or_b64 exec, exec, s[10:11]
	s_nop 0
	v_lshl_add_u32 v142, v145, 4, v199
	s_waitcnt vmcnt(3)
	v_fmamk_f32 v132, v208, 0x3b800000, v194
	v_cmp_gt_f32_e64 s[42:43], s19, v132
	s_waitcnt lgkmcnt(0)
	v_mul_f32_e32 v133, 0x4b800000, v132
	v_cndmask_b32_e64 v132, v132, v133, s[42:43]
	v_rsq_f32_e32 v132, v132
	s_nop 0
	v_mul_f32_e32 v133, 0x45800000, v132
	v_cndmask_b32_e64 v132, v132, v133, s[42:43]
	v_pk_mul_f32 v[140:141], v[60:61], v[132:133] op_sel_hi:[1,0]
	v_pk_mul_f32 v[138:139], v[62:63], v[132:133] op_sel_hi:[1,0]
	v_mul_f32_e32 v133, v141, v141
	v_fmac_f32_e32 v133, v140, v140
	v_fmac_f32_e32 v133, v138, v138
	v_fmac_f32_e32 v133, v139, v139
	v_pk_mul_f32 v[140:141], v[56:57], v[132:133] op_sel_hi:[1,0]
	v_pk_mul_f32 v[138:139], v[58:59], v[132:133] op_sel_hi:[1,0]
	v_mul_f32_e32 v141, v141, v141
	v_fmac_f32_e32 v141, v140, v140
	v_fmac_f32_e32 v141, v138, v138
	v_fmac_f32_e32 v141, v139, v139
	v_add_f32_e32 v133, v133, v141
	ds_bpermute_b32 v138, v135, v133
	s_waitcnt lgkmcnt(0)
	v_add_f32_e32 v133, v133, v138
	ds_bpermute_b32 v139, v136, v133
	v_add_u32_e32 v138, v137, v142
	s_and_saveexec_b64 s[10:11], vcc
	s_cbranch_execz .LBB0_976
	s_waitcnt lgkmcnt(0)
	v_add_f32_e32 v133, v133, v139
	ds_write_b32 v138, v133 offset:32768

.LBB0_978:
	s_or_b64 exec, exec, s[10:11]
	s_nop 0
	s_waitcnt vmcnt(2)
	v_fmamk_f32 v132, v209, 0x3b800000, v194
	v_cmp_gt_f32_e64 s[42:43], s19, v132
	s_waitcnt lgkmcnt(0)
	v_mul_f32_e32 v133, 0x4b800000, v132
	v_cndmask_b32_e64 v132, v132, v133, s[42:43]
	v_rsq_f32_e32 v132, v132
	s_nop 0
	v_mul_f32_e32 v133, 0x45800000, v132
	v_cndmask_b32_e64 v132, v132, v133, s[42:43]
	v_mov_b32_e32 v133, 0x900
	v_pk_mul_f32 v[140:141], v[44:45], v[132:133] op_sel_hi:[1,0]
	v_lshl_add_u32 v142, v145, 4, v133
	v_pk_mul_f32 v[138:139], v[46:47], v[132:133] op_sel_hi:[1,0]
	v_mul_f32_e32 v133, v141, v141
	v_fmac_f32_e32 v133, v140, v140
	v_fmac_f32_e32 v133, v138, v138
	v_fmac_f32_e32 v133, v139, v139
	v_pk_mul_f32 v[140:141], v[40:41], v[132:133] op_sel_hi:[1,0]
	v_pk_mul_f32 v[138:139], v[42:43], v[132:133] op_sel_hi:[1,0]
	v_mul_f32_e32 v141, v141, v141
	v_fmac_f32_e32 v141, v140, v140
	v_fmac_f32_e32 v141, v138, v138
	v_fmac_f32_e32 v141, v139, v139
	v_add_f32_e32 v133, v133, v141
	ds_bpermute_b32 v138, v135, v133
	s_waitcnt lgkmcnt(0)
	v_add_f32_e32 v133, v133, v138
	ds_bpermute_b32 v139, v136, v133
	v_add_u32_e32 v138, v137, v142
	s_and_saveexec_b64 s[10:11], vcc
	s_cbranch_execz .LBB0_980
	s_waitcnt lgkmcnt(0)
	v_add_f32_e32 v133, v133, v139
	ds_write_b32 v138, v133 offset:32768

.LBB0_982:
	s_or_b64 exec, exec, s[10:11]
	s_nop 0
	s_waitcnt vmcnt(1)
	v_fmamk_f32 v132, v210, 0x3b800000, v194
	v_cmp_gt_f32_e64 s[42:43], s19, v132
	s_waitcnt lgkmcnt(0)
	v_mul_f32_e32 v133, 0x4b800000, v132
	v_cndmask_b32_e64 v132, v132, v133, s[42:43]
	v_rsq_f32_e32 v132, v132
	s_nop 0
	v_mul_f32_e32 v133, 0x45800000, v132
	v_cndmask_b32_e64 v132, v132, v133, s[42:43]
	v_mov_b32_e32 v133, 0xa00
	v_pk_mul_f32 v[140:141], v[28:29], v[132:133] op_sel_hi:[1,0]
	v_lshl_add_u32 v142, v145, 4, v133
	v_pk_mul_f32 v[138:139], v[30:31], v[132:133] op_sel_hi:[1,0]
	v_mul_f32_e32 v133, v141, v141
	v_fmac_f32_e32 v133, v140, v140
	v_fmac_f32_e32 v133, v138, v138
	v_fmac_f32_e32 v133, v139, v139
	v_pk_mul_f32 v[140:141], v[24:25], v[132:133] op_sel_hi:[1,0]
	v_pk_mul_f32 v[138:139], v[26:27], v[132:133] op_sel_hi:[1,0]
	v_mul_f32_e32 v141, v141, v141
	v_fmac_f32_e32 v141, v140, v140
	v_fmac_f32_e32 v141, v138, v138
	v_fmac_f32_e32 v141, v139, v139
	v_add_f32_e32 v133, v133, v141
	ds_bpermute_b32 v138, v135, v133
	s_waitcnt lgkmcnt(0)
	v_add_f32_e32 v133, v133, v138
	ds_bpermute_b32 v139, v136, v133
	v_add_u32_e32 v138, v137, v142
	s_and_saveexec_b64 s[10:11], vcc
	s_cbranch_execz .LBB0_984
	s_waitcnt lgkmcnt(0)
	v_add_f32_e32 v133, v133, v139
	ds_write_b32 v138, v133 offset:32768

.LBB0_986:
	s_or_b64 exec, exec, s[10:11]
	s_nop 0
	s_waitcnt vmcnt(0)
	v_fmamk_f32 v82, v211, 0x3b800000, v194
	v_cmp_gt_f32_e64 s[42:43], s19, v82
	v_mul_f32_e32 v83, 0x4b800000, v82
	s_nop 0
	v_cndmask_b32_e64 v82, v82, v83, s[42:43]
	v_rsq_f32_e32 v82, v82
	s_nop 0
	v_mul_f32_e32 v83, 0x45800000, v82
	v_cndmask_b32_e64 v82, v82, v83, s[42:43]
	v_mov_b32_e32 v83, 0xb00
	v_pk_mul_f32 v[138:139], v[12:13], v[82:83] op_sel_hi:[1,0]
	v_lshl_add_u32 v140, v145, 4, v83
	s_waitcnt lgkmcnt(0)
	v_pk_mul_f32 v[132:133], v[14:15], v[82:83] op_sel_hi:[1,0]
	v_mul_f32_e32 v83, v139, v139
	v_fmac_f32_e32 v83, v138, v138
	v_fmac_f32_e32 v83, v132, v132
	v_fmac_f32_e32 v83, v133, v133
	v_pk_mul_f32 v[138:139], v[8:9], v[82:83] op_sel_hi:[1,0]
	v_pk_mul_f32 v[132:133], v[10:11], v[82:83] op_sel_hi:[1,0]
	v_mul_f32_e32 v139, v139, v139
	v_fmac_f32_e32 v139, v138, v138
	v_fmac_f32_e32 v139, v132, v132
	v_fmac_f32_e32 v139, v133, v133
	v_add_f32_e32 v83, v83, v139
	ds_bpermute_b32 v132, v135, v83
	s_waitcnt lgkmcnt(0)
	v_add_f32_e32 v83, v83, v132
	ds_bpermute_b32 v133, v136, v83
	v_add_u32_e32 v132, v137, v140
	s_and_saveexec_b64 s[10:11], vcc
	s_cbranch_execz .LBB0_988
	s_waitcnt lgkmcnt(0)
	v_add_f32_e32 v83, v83, v133
	ds_write_b32 v132, v83 offset:32768
